# grid barrier last-arriver path: no wait between the generation update and the L1 invalidate (on top of global-word polling)
# baseline (speedup 1.0000x reference)
.LBB0_177:
	s_or_b64 exec, exec, s[6:7]
	s_mov_b64 s[6:7], exec
	v_mbcnt_lo_u32_b32 v0, s6, 0
	v_mbcnt_hi_u32_b32 v0, s7, v0
	v_cmp_eq_u32_e32 vcc, 0, v0
	buffer_inv sc1
	s_and_saveexec_b64 s[12:13], vcc
	s_cbranch_execz .LBB0_179
	s_bcnt1_i32_b64 s2, s[6:7]
	v_mov_b32_e32 v0, 0x2000
	v_mov_b32_e32 v1, s2
	global_atomic_add v0, v1, s[8:9] offset:1024

.LBB0_295:
	s_or_b64 exec, exec, s[6:7]
	s_mov_b64 s[6:7], exec
	v_mbcnt_lo_u32_b32 v0, s6, 0
	v_mbcnt_hi_u32_b32 v0, s7, v0
	v_cmp_eq_u32_e32 vcc, 0, v0
	buffer_inv sc1
	s_and_saveexec_b64 s[12:13], vcc
	s_cbranch_execz .LBB0_297
	s_bcnt1_i32_b64 s3, s[6:7]
	v_mov_b32_e32 v0, 0x2000
	v_mov_b32_e32 v1, s3
	global_atomic_add v0, v1, s[8:9] offset:1024

.LBB0_445:
	s_or_b64 exec, exec, s[4:5]
	s_mov_b64 s[4:5], exec
	v_mbcnt_lo_u32_b32 v0, s4, 0
	v_mbcnt_hi_u32_b32 v0, s5, v0
	v_cmp_eq_u32_e32 vcc, 0, v0
	buffer_inv sc1
	s_and_saveexec_b64 s[10:11], vcc
	s_cbranch_execz .LBB0_447
	s_bcnt1_i32_b64 s4, s[4:5]
	v_mov_b32_e32 v0, 0x2000
	v_mov_b32_e32 v1, s4
	global_atomic_add v0, v1, s[6:7] offset:1024

.LBB0_587:
	s_or_b64 exec, exec, s[4:5]
	s_mov_b64 s[4:5], exec
	v_mbcnt_lo_u32_b32 v0, s4, 0
	v_mbcnt_hi_u32_b32 v0, s5, v0
	v_cmp_eq_u32_e32 vcc, 0, v0
	buffer_inv sc1
	s_and_saveexec_b64 s[8:9], vcc
	s_cbranch_execz .LBB0_589
	s_bcnt1_i32_b64 s4, s[4:5]
	v_mov_b32_e32 v0, 0x2000
	v_mov_b32_e32 v1, s4
	global_atomic_add v0, v1, s[6:7] offset:1024

.LBB0_703:
	s_or_b64 exec, exec, s[6:7]
	s_mov_b64 s[6:7], exec
	v_mbcnt_lo_u32_b32 v0, s6, 0
	v_mbcnt_hi_u32_b32 v0, s7, v0
	v_cmp_eq_u32_e32 vcc, 0, v0
	buffer_inv sc1
	s_and_saveexec_b64 s[12:13], vcc
	s_cbranch_execz .LBB0_705
	s_bcnt1_i32_b64 s6, s[6:7]
	v_mov_b32_e32 v0, 0x2000
	v_mov_b32_e32 v1, s6
	global_atomic_add v0, v1, s[8:9] offset:1024
